# prologue: in-proj weight transposes as a software-pipelined loop (two tiles in flight) + ada_w rows pre-touched for the modulation item
# speedup vs baseline: 1.0024x; 1.0024x over previous
; DEV void transpose_item(const float* __restrict__ src, int N, int K, u16* __restrict__ dst,
;                         const float* __restrict__ gain, int tn, int tk, char* smem, int tid) {
;   float* tile = (float*)smem;
;   __syncthreads();
; #pragma unroll
;   for (int i = 0; i < 2; ++i) {
;     int kk = (tid >> 4) + 32 * i, n4 = (tid & 15) * 4;
;     int k = tk * 64 + kk, n = tn * 64 + n4;
;     float4 v = make_float4(0.f, 0.f, 0.f, 0.f);
;     if (n < N) v = *(const float4*)(src + (long)k * N + n);
;     float gsc = gain ? gain[k] : 1.f;
;     tile[kk * 65 + n4 + 0] = v.x * gsc;
;     tile[kk * 65 + n4 + 1] = v.y * gsc;
;     tile[kk * 65 + n4 + 2] = v.z * gsc;
;     tile[kk * 65 + n4 + 3] = v.w * gsc;
;   }
;   __syncthreads();
.LBB0_5:
	s_or_b64 exec, exec, s[8:9]
	v_writelane_b32 v253, s2, 6
	s_cmpk_gt_i32 s2, 0x2e00
	s_cbranch_scc1 .LBB0_89
	v_readlane_b32 s0, v253, 0
	v_readlane_b32 s1, v253, 1
	s_load_dwordx16 s[12:27], s[0:1], 0xa0
	s_load_dwordx8 s[52:59], s[0:1], 0x38
	s_load_dwordx4 s[4:7], s[0:1], 0x80
	s_load_dwordx4 s[44:47], s[0:1], 0x58
	s_load_dwordx2 s[2:3], s[0:1], 0x8
	s_load_dwordx4 s[48:51], s[0:1], 0x18
	s_mov_b32 s43, 0
	v_mov_b32_e32 v11, 0
	s_waitcnt lgkmcnt(0)
	s_cmp_lg_u64 s[56:57], 0
	v_writelane_b32 v253, s4, 7
	s_cselect_b64 s[34:35], -1, 0
	s_cmp_lg_u64 s[54:55], 0
	v_writelane_b32 v253, s5, 8
	v_writelane_b32 v253, s6, 9
	v_writelane_b32 v253, s7, 10
	s_cselect_b64 s[38:39], -1, 0
	s_add_u32 s40, s50, 0x603000
	s_addc_u32 s41, s51, 0
	s_movk_i32 s68, 0x104
	v_cndmask_b32_e64 v1, 0, 1, s[34:35]
	s_movk_i32 s69, 0xc00
	v_cndmask_b32_e64 v46, 0, 1, s[38:39]
	s_mov_b32 s70, 0x8680
	s_movk_i32 s71, 0x3000
	s_mov_b32 s72, 0x3fb8aa3b
	s_mov_b32 s73, 0xc2ce8ed0
	s_mov_b32 s74, 0x42b17218
	s_movk_i32 s75, 0x1ff
	v_mov_b32_e32 v47, 0x3e91f4c4
	s_movk_i32 s76, 0x204
	s_mov_b32 s77, 0xfe5163ab
	s_mov_b32 s78, 0x3c439041
	s_mov_b32 s79, 0xdb629599
	s_mov_b32 s80, 0xf534ddc0
	s_mov_b32 s81, 0xfc2757d1
	s_mov_b32 s82, 0x4e441529
	s_mov_b32 s83, 0xa2f9836e
	s_mov_b32 s84, 0x3fc90fda
	s_mov_b32 s85, 0xbfc90fda
	v_mov_b32_e32 v48, 0x3c0881c4
	v_mov_b32_e32 v49, 0xbab64f3b
	s_brev_b32 s86, 1
	s_movk_i32 s87, 0x1f8
	s_movk_i32 s88, 0x4200
	s_mov_b32 s89, 0xbfb8aa3b
	s_mov_b32 s90, 0x42ce8ed0
	s_mov_b32 s91, 0xc2b17218
	s_movk_i32 s92, 0x3fff
	s_mov_b64 s[60:61], 0x6000
	s_movk_i32 s93, 0xd000
	s_movk_i32 s94, 0x2100
	s_movk_i32 s95, 0x840
	s_movk_i32 s96, 0x63f
	v_mov_b32_e32 v50, 0x7f800000
	v_mov_b32_e32 v51, 0x461c4000
	v_mov_b32_e32 v52, 0x37000000
	v_not_b32_e32 v53, 63
	v_not_b32_e32 v54, 31
	v_mov_b32_e32 v55, 0x7fc00000
	v_readlane_b32 s97, v253, 6
	v_and_b32_e32 v112, 15, v197
	v_lshlrev_b32_e32 v112, 2, v112
	v_lshrrev_b32_e32 v113, 4, v197
	v_mul_u32_u24_e32 v80, 0x8680, v113
	v_mul_u32_u24_e32 v81, 0x41, v113
	v_add_u32_e32 v81, v81, v112
	v_lshlrev_b32_e32 v81, 2, v81
	v_lshrrev_b32_e32 v113, 3, v197
	v_and_b32_e32 v114, 7, v197
	v_lshlrev_b32_e32 v114, 3, v114
	v_mul_u32_u24_e32 v82, 0x41, v114
	v_add_u32_e32 v82, v82, v113
	v_lshlrev_b32_e32 v82, 2, v82
	v_lshl_add_u32 v83, v113, 10, v114
	v_lshlrev_b32_e32 v83, 1, v83
	v_readlane_b32 s30, v253, 6
	s_lshr_b32 s0, s30, 7
	s_mul_i32 s0, s0, 241
	s_lshr_b32 s0, s0, 12
	s_mul_i32 s4, s0, 0x880
	s_sub_i32 s4, s30, s4
	s_and_b32 s5, s4, 15
	s_lshr_b32 s4, s4, 4
	s_min_u32 s4, s4, 134
	s_lshl_b32 s9, s0, 10
	s_lshl_b32 s10, s5, 6
	s_add_i32 s9, s9, s10
	s_mul_i32 s9, s9, 0x8680
	s_lshl_b32 s10, s4, 8
	s_add_u32 s9, s9, s10
	s_add_u32 s62, s52, s9
	s_addc_u32 s63, s53, 0
	s_add_u32 s64, s62, 0x10d000
	s_addc_u32 s65, s63, 0
	s_lshl_b32 s10, s4, 6
	s_sub_i32 s10, 0x219c, s10
	v_min_u32_e32 v121, s10, v112
	v_lshl_add_u32 v122, v121, 2, v80
	global_load_dwordx4 v[64:67], v122, s[62:63]
	global_load_dwordx4 v[68:71], v122, s[64:65]
	s_add_i32 s42, s30, 0x100
	s_lshr_b32 s0, s42, 7
	s_mul_i32 s0, s0, 241
	s_lshr_b32 s0, s0, 12
	s_mul_i32 s4, s0, 0x880
	s_sub_i32 s4, s42, s4
	s_and_b32 s5, s4, 15
	s_lshr_b32 s4, s4, 4
	s_min_u32 s4, s4, 134
	s_lshl_b32 s9, s0, 10
	s_lshl_b32 s10, s5, 6
	s_add_i32 s9, s9, s10
	s_mul_i32 s9, s9, 0x8680
	s_lshl_b32 s10, s4, 8
	s_add_u32 s9, s9, s10
	s_add_u32 s62, s52, s9
	s_addc_u32 s63, s53, 0
	s_add_u32 s64, s62, 0x10d000
	s_addc_u32 s65, s63, 0
	s_lshl_b32 s10, s4, 6
	s_sub_i32 s10, 0x219c, s10
	v_min_u32_e32 v121, s10, v112
	v_lshl_add_u32 v122, v121, 2, v80
	global_load_dwordx4 v[72:75], v122, s[62:63]
	global_load_dwordx4 v[76:79], v122, s[64:65]
	s_lshr_b32 s11, s30, 7
	s_mul_i32 s11, s11, 241
	s_lshr_b32 s11, s11, 12
	s_mul_i32 s31, s11, 0x880
	s_sub_i32 s31, s30, s31
	s_and_b32 s32, s31, 15
	s_lshr_b32 s31, s31, 4
	s_lshl_b32 s9, s31, 6
	s_sub_i32 s9, 0x21a0, s9
	v_cmp_gt_i32_e32 vcc, s9, v112
	s_waitcnt vmcnt(2)
	s_nop 1
	v_cndmask_b32_e32 v64, 0, v64, vcc
	v_cndmask_b32_e32 v65, 0, v65, vcc
	v_cndmask_b32_e32 v66, 0, v66, vcc
	v_cndmask_b32_e32 v67, 0, v67, vcc
	v_cndmask_b32_e32 v68, 0, v68, vcc
	v_cndmask_b32_e32 v69, 0, v69, vcc
	v_cndmask_b32_e32 v70, 0, v70, vcc
	v_cndmask_b32_e32 v71, 0, v71, vcc
	ds_write_b32 v81, v64 offset:0
	ds_write_b32 v81, v65 offset:4
	ds_write_b32 v81, v66 offset:8
	ds_write_b32 v81, v67 offset:12
	ds_write_b32 v81, v68 offset:8320
	ds_write_b32 v81, v69 offset:8324
	ds_write_b32 v81, v70 offset:8328
	ds_write_b32 v81, v71 offset:8332
	s_add_i32 s42, s30, 0x200
	s_cmpk_lt_u32 s42, 0x2200
	s_cselect_b32 s42, s42, s30
	s_lshr_b32 s0, s42, 7
	s_mul_i32 s0, s0, 241
	s_lshr_b32 s0, s0, 12
	s_mul_i32 s4, s0, 0x880
	s_sub_i32 s4, s42, s4
	s_and_b32 s5, s4, 15
	s_lshr_b32 s4, s4, 4
	s_min_u32 s4, s4, 134
	s_lshl_b32 s9, s0, 10
	s_lshl_b32 s10, s5, 6
	s_add_i32 s9, s9, s10
	s_mul_i32 s9, s9, 0x8680
	s_lshl_b32 s10, s4, 8
	s_add_u32 s9, s9, s10
	s_add_u32 s62, s52, s9
	s_addc_u32 s63, s53, 0
	s_add_u32 s64, s62, 0x10d000
	s_addc_u32 s65, s63, 0
	s_lshl_b32 s10, s4, 6
	s_sub_i32 s10, 0x219c, s10
	v_min_u32_e32 v121, s10, v112
	v_lshl_add_u32 v122, v121, 2, v80
	global_load_dwordx4 v[64:67], v122, s[62:63]
	global_load_dwordx4 v[68:71], v122, s[64:65]
	s_waitcnt lgkmcnt(0)
	s_barrier
; DEV void transpose_item(const float* __restrict__ src, int N, int K, u16* __restrict__ dst,
;                         const float* __restrict__ gain, int tn, int tk, char* smem, int tid) {
;     ...
;   __syncthreads();
;   int n = tid >> 3, kc = (tid & 7) * 8;
;   uint4 o;
;   o.x = pack2(tile[(kc + 0) * 65 + n], tile[(kc + 1) * 65 + n]);
;   o.y = pack2(tile[(kc + 2) * 65 + n], tile[(kc + 3) * 65 + n]);
;   o.z = pack2(tile[(kc + 4) * 65 + n], tile[(kc + 5) * 65 + n]);
;   o.w = pack2(tile[(kc + 6) * 65 + n], tile[(kc + 7) * 65 + n]);
;   *(uint4*)(dst + (long)(tn * 64 + n) * K + tk * 64 + kc) = o;
	ds_read_b32 v113, v82 offset:0
	ds_read_b32 v114, v82 offset:260
	ds_read_b32 v115, v82 offset:520
	ds_read_b32 v116, v82 offset:780
	ds_read_b32 v117, v82 offset:1040
	ds_read_b32 v118, v82 offset:1300
	ds_read_b32 v119, v82 offset:1560
	ds_read_b32 v120, v82 offset:1820
	s_mul_i32 s9, s11, 0x2200
	s_lshl_b32 s10, s31, 6
	s_add_i32 s9, s9, s10
	s_lshl_b32 s9, s9, 11
	s_lshl_b32 s10, s32, 7
	s_add_u32 s9, s9, s10
	s_add_u32 s66, s12, s9
	s_addc_u32 s67, s13, 0
	s_waitcnt lgkmcnt(0)
	v_cvt_pk_bf16_f32 v128, v113, v114
	v_cvt_pk_bf16_f32 v129, v115, v116
	v_cvt_pk_bf16_f32 v130, v117, v118
	v_cvt_pk_bf16_f32 v131, v119, v120
	global_store_dwordx4 v83, v[128:131], s[66:67]
	s_addk_i32 s30, 0x100
	s_lshr_b32 s11, s30, 7
	s_mul_i32 s11, s11, 241
	s_lshr_b32 s11, s11, 12
	s_mul_i32 s31, s11, 0x880
	s_sub_i32 s31, s30, s31
	s_and_b32 s32, s31, 15
	s_lshr_b32 s31, s31, 4
	s_lshl_b32 s9, s31, 6
	s_sub_i32 s9, 0x21a0, s9
	v_cmp_gt_i32_e32 vcc, s9, v112
	s_waitcnt vmcnt(3)
	s_nop 1
	v_cndmask_b32_e32 v72, 0, v72, vcc
	v_cndmask_b32_e32 v73, 0, v73, vcc
	v_cndmask_b32_e32 v74, 0, v74, vcc
	v_cndmask_b32_e32 v75, 0, v75, vcc
	v_cndmask_b32_e32 v76, 0, v76, vcc
	v_cndmask_b32_e32 v77, 0, v77, vcc
	v_cndmask_b32_e32 v78, 0, v78, vcc
	v_cndmask_b32_e32 v79, 0, v79, vcc
	ds_write_b32 v81, v72 offset:16640
	ds_write_b32 v81, v73 offset:16644
	ds_write_b32 v81, v74 offset:16648
	ds_write_b32 v81, v75 offset:16652
	ds_write_b32 v81, v76 offset:24960
	ds_write_b32 v81, v77 offset:24964
	ds_write_b32 v81, v78 offset:24968
	ds_write_b32 v81, v79 offset:24972
	s_add_i32 s42, s30, 0x200
	s_cmpk_lt_u32 s42, 0x2200
	s_cselect_b32 s42, s42, s30
	s_lshr_b32 s0, s42, 7
	s_mul_i32 s0, s0, 241
	s_lshr_b32 s0, s0, 12
	s_mul_i32 s4, s0, 0x880
	s_sub_i32 s4, s42, s4
	s_and_b32 s5, s4, 15
	s_lshr_b32 s4, s4, 4
	s_min_u32 s4, s4, 134
	s_lshl_b32 s9, s0, 10
	s_lshl_b32 s10, s5, 6
	s_add_i32 s9, s9, s10
	s_mul_i32 s9, s9, 0x8680
	s_lshl_b32 s10, s4, 8
	s_add_u32 s9, s9, s10
	s_add_u32 s62, s52, s9
	s_addc_u32 s63, s53, 0
	s_add_u32 s64, s62, 0x10d000
	s_addc_u32 s65, s63, 0
	s_lshl_b32 s10, s4, 6
	s_sub_i32 s10, 0x219c, s10
	v_min_u32_e32 v121, s10, v112
	v_lshl_add_u32 v122, v121, 2, v80
	global_load_dwordx4 v[72:75], v122, s[62:63]
	global_load_dwordx4 v[76:79], v122, s[64:65]
	s_waitcnt lgkmcnt(0)
	s_barrier
	ds_read_b32 v113, v82 offset:16640
	ds_read_b32 v114, v82 offset:16900
	ds_read_b32 v115, v82 offset:17160
	ds_read_b32 v116, v82 offset:17420
	ds_read_b32 v117, v82 offset:17680
	ds_read_b32 v118, v82 offset:17940
	ds_read_b32 v119, v82 offset:18200
	ds_read_b32 v120, v82 offset:18460
	s_mul_i32 s9, s11, 0x2200
	s_lshl_b32 s10, s31, 6
	s_add_i32 s9, s9, s10
	s_lshl_b32 s9, s9, 11
	s_lshl_b32 s10, s32, 7
	s_add_u32 s9, s9, s10
	s_add_u32 s66, s12, s9
	s_addc_u32 s67, s13, 0
	s_waitcnt lgkmcnt(0)
	v_cvt_pk_bf16_f32 v128, v113, v114
	v_cvt_pk_bf16_f32 v129, v115, v116
	v_cvt_pk_bf16_f32 v130, v117, v118
	v_cvt_pk_bf16_f32 v131, v119, v120
	global_store_dwordx4 v83, v[128:131], s[66:67]
	s_addk_i32 s30, 0x100
; DEV void transpose_item(const float* __restrict__ src, int N, int K, u16* __restrict__ dst,
;                         const float* __restrict__ gain, int tn, int tk, char* smem, int tid) {
;   float* tile = (float*)smem;
;   __syncthreads();
; #pragma unroll
;   for (int i = 0; i < 2; ++i) {
;     int kk = (tid >> 4) + 32 * i, n4 = (tid & 15) * 4;
;     int k = tk * 64 + kk, n = tn * 64 + n4;
;     float4 v = make_float4(0.f, 0.f, 0.f, 0.f);
;     if (n < N) v = *(const float4*)(src + (long)k * N + n);
;     float gsc = gain ? gain[k] : 1.f;
;     tile[kk * 65 + n4 + 0] = v.x * gsc;
;     tile[kk * 65 + n4 + 1] = v.y * gsc;
;     tile[kk * 65 + n4 + 2] = v.z * gsc;
;     tile[kk * 65 + n4 + 3] = v.w * gsc;
;   }
;   __syncthreads();
;   int n = tid >> 3, kc = (tid & 7) * 8;
;   uint4 o;
;   o.x = pack2(tile[(kc + 0) * 65 + n], tile[(kc + 1) * 65 + n]);
;   o.y = pack2(tile[(kc + 2) * 65 + n], tile[(kc + 3) * 65 + n]);
;   o.z = pack2(tile[(kc + 4) * 65 + n], tile[(kc + 5) * 65 + n]);
;   o.w = pack2(tile[(kc + 6) * 65 + n], tile[(kc + 7) * 65 + n]);
;   *(uint4*)(dst + (long)(tn * 64 + n) * K + tk * 64 + kc) = o;
.Lpre_win_loop:
	s_lshr_b32 s11, s30, 7
	s_mul_i32 s11, s11, 241
	s_lshr_b32 s11, s11, 12
	s_mul_i32 s31, s11, 0x880
	s_sub_i32 s31, s30, s31
	s_and_b32 s32, s31, 15
	s_lshr_b32 s31, s31, 4
	s_lshl_b32 s9, s31, 6
	s_sub_i32 s9, 0x21a0, s9
	v_cmp_gt_i32_e32 vcc, s9, v112
	s_waitcnt vmcnt(4)
	s_nop 1
	v_cndmask_b32_e32 v64, 0, v64, vcc
	v_cndmask_b32_e32 v65, 0, v65, vcc
	v_cndmask_b32_e32 v66, 0, v66, vcc
	v_cndmask_b32_e32 v67, 0, v67, vcc
	v_cndmask_b32_e32 v68, 0, v68, vcc
	v_cndmask_b32_e32 v69, 0, v69, vcc
	v_cndmask_b32_e32 v70, 0, v70, vcc
	v_cndmask_b32_e32 v71, 0, v71, vcc
	ds_write_b32 v81, v64 offset:0
	ds_write_b32 v81, v65 offset:4
	ds_write_b32 v81, v66 offset:8
	ds_write_b32 v81, v67 offset:12
	ds_write_b32 v81, v68 offset:8320
	ds_write_b32 v81, v69 offset:8324
	ds_write_b32 v81, v70 offset:8328
	ds_write_b32 v81, v71 offset:8332
	s_add_i32 s42, s30, 0x200
	s_cmpk_lt_u32 s42, 0x2200
	s_cselect_b32 s42, s42, s30
	s_lshr_b32 s0, s42, 7
	s_mul_i32 s0, s0, 241
	s_lshr_b32 s0, s0, 12
	s_mul_i32 s4, s0, 0x880
	s_sub_i32 s4, s42, s4
	s_and_b32 s5, s4, 15
	s_lshr_b32 s4, s4, 4
	s_min_u32 s4, s4, 134
	s_lshl_b32 s9, s0, 10
	s_lshl_b32 s10, s5, 6
	s_add_i32 s9, s9, s10
	s_mul_i32 s9, s9, 0x8680
	s_lshl_b32 s10, s4, 8
	s_add_u32 s9, s9, s10
	s_add_u32 s62, s52, s9
	s_addc_u32 s63, s53, 0
	s_add_u32 s64, s62, 0x10d000
	s_addc_u32 s65, s63, 0
	s_lshl_b32 s10, s4, 6
	s_sub_i32 s10, 0x219c, s10
	v_min_u32_e32 v121, s10, v112
	v_lshl_add_u32 v122, v121, 2, v80
	global_load_dwordx4 v[64:67], v122, s[62:63]
	global_load_dwordx4 v[68:71], v122, s[64:65]
	s_waitcnt lgkmcnt(0)
	s_barrier
	ds_read_b32 v113, v82 offset:0
	ds_read_b32 v114, v82 offset:260
	ds_read_b32 v115, v82 offset:520
	ds_read_b32 v116, v82 offset:780
	ds_read_b32 v117, v82 offset:1040
	ds_read_b32 v118, v82 offset:1300
	ds_read_b32 v119, v82 offset:1560
	ds_read_b32 v120, v82 offset:1820
	s_mul_i32 s9, s11, 0x2200
	s_lshl_b32 s10, s31, 6
	s_add_i32 s9, s9, s10
	s_lshl_b32 s9, s9, 11
	s_lshl_b32 s10, s32, 7
	s_add_u32 s9, s9, s10
	s_add_u32 s66, s12, s9
	s_addc_u32 s67, s13, 0
	s_waitcnt lgkmcnt(0)
	v_cvt_pk_bf16_f32 v128, v113, v114
	v_cvt_pk_bf16_f32 v129, v115, v116
	v_cvt_pk_bf16_f32 v130, v117, v118
	v_cvt_pk_bf16_f32 v131, v119, v120
	global_store_dwordx4 v83, v[128:131], s[66:67]
	s_addk_i32 s30, 0x100
	s_lshr_b32 s11, s30, 7
	s_mul_i32 s11, s11, 241
	s_lshr_b32 s11, s11, 12
	s_mul_i32 s31, s11, 0x880
	s_sub_i32 s31, s30, s31
	s_and_b32 s32, s31, 15
	s_lshr_b32 s31, s31, 4
	s_lshl_b32 s9, s31, 6
	s_sub_i32 s9, 0x21a0, s9
	v_cmp_gt_i32_e32 vcc, s9, v112
	s_waitcnt vmcnt(4)
	s_nop 1
	v_cndmask_b32_e32 v72, 0, v72, vcc
	v_cndmask_b32_e32 v73, 0, v73, vcc
	v_cndmask_b32_e32 v74, 0, v74, vcc
	v_cndmask_b32_e32 v75, 0, v75, vcc
	v_cndmask_b32_e32 v76, 0, v76, vcc
	v_cndmask_b32_e32 v77, 0, v77, vcc
	v_cndmask_b32_e32 v78, 0, v78, vcc
	v_cndmask_b32_e32 v79, 0, v79, vcc
	ds_write_b32 v81, v72 offset:16640
	ds_write_b32 v81, v73 offset:16644
	ds_write_b32 v81, v74 offset:16648
	ds_write_b32 v81, v75 offset:16652
	ds_write_b32 v81, v76 offset:24960
	ds_write_b32 v81, v77 offset:24964
	ds_write_b32 v81, v78 offset:24968
	ds_write_b32 v81, v79 offset:24972
	s_add_i32 s42, s30, 0x200
	s_cmpk_lt_u32 s42, 0x2200
	s_cselect_b32 s42, s42, s30
	s_lshr_b32 s0, s42, 7
	s_mul_i32 s0, s0, 241
	s_lshr_b32 s0, s0, 12
	s_mul_i32 s4, s0, 0x880
	s_sub_i32 s4, s42, s4
	s_and_b32 s5, s4, 15
	s_lshr_b32 s4, s4, 4
	s_min_u32 s4, s4, 134
	s_lshl_b32 s9, s0, 10
	s_lshl_b32 s10, s5, 6
	s_add_i32 s9, s9, s10
	s_mul_i32 s9, s9, 0x8680
	s_lshl_b32 s10, s4, 8
	s_add_u32 s9, s9, s10
	s_add_u32 s62, s52, s9
	s_addc_u32 s63, s53, 0
	s_add_u32 s64, s62, 0x10d000
	s_addc_u32 s65, s63, 0
	s_lshl_b32 s10, s4, 6
	s_sub_i32 s10, 0x219c, s10
	v_min_u32_e32 v121, s10, v112
	v_lshl_add_u32 v122, v121, 2, v80
	global_load_dwordx4 v[72:75], v122, s[62:63]
	global_load_dwordx4 v[76:79], v122, s[64:65]
	s_waitcnt lgkmcnt(0)
	s_barrier
	ds_read_b32 v113, v82 offset:16640
	ds_read_b32 v114, v82 offset:16900
	ds_read_b32 v115, v82 offset:17160
	ds_read_b32 v116, v82 offset:17420
	ds_read_b32 v117, v82 offset:17680
	ds_read_b32 v118, v82 offset:17940
	ds_read_b32 v119, v82 offset:18200
	ds_read_b32 v120, v82 offset:18460
	s_mul_i32 s9, s11, 0x2200
	s_lshl_b32 s10, s31, 6
	s_add_i32 s9, s9, s10
	s_lshl_b32 s9, s9, 11
	s_lshl_b32 s10, s32, 7
	s_add_u32 s9, s9, s10
	s_add_u32 s66, s12, s9
	s_addc_u32 s67, s13, 0
	s_waitcnt lgkmcnt(0)
	v_cvt_pk_bf16_f32 v128, v113, v114
	v_cvt_pk_bf16_f32 v129, v115, v116
	v_cvt_pk_bf16_f32 v130, v117, v118
	v_cvt_pk_bf16_f32 v131, v119, v120
	global_store_dwordx4 v83, v[128:131], s[66:67]
	s_addk_i32 s30, 0x100
	s_cmpk_lt_u32 s30, 0x2200
	s_cbranch_scc1 .Lpre_win_loop
	s_waitcnt vmcnt(0)
	s_barrier
	s_branch .LBB0_9
